# side workgroups (no out-proj tile) arrive at the post-mixer barrier but do not wait for it, starting the next layer's shift-bias work at once; one local counter word per barrier instance
# speedup vs baseline: 1.0100x; 1.0075x over previous
.LBB0_811:
	s_mov_b32 s6, s71
	s_waitcnt vmcnt(0)
	s_waitcnt lgkmcnt(0)
	s_barrier
	s_and_saveexec_b64 s[0:1], s[26:27]
	s_cbranch_execz .LBB0_848
	v_readlane_b32 s7, v255, 17
	s_waitcnt vmcnt(0) expcnt(0) lgkmcnt(0)
	s_mov_b64 s[4:5], exec
	v_mov_b32_e32 v0, s7
	v_readlane_b32 s7, v255, 18
	ds_read_b32 v2, v0
	v_mbcnt_lo_u32_b32 v1, s4, 0
	v_mov_b32_e32 v0, s7
	ds_read_b32 v0, v0
	v_mbcnt_hi_u32_b32 v1, s5, v1
	s_lshl_b32 s20, s6, 6
	v_cmp_eq_u32_e32 vcc, 0, v1
	s_and_saveexec_b64 s[6:7], vcc
	s_cbranch_execz .LBB0_814
	s_add_i32 s96, s20, 0x500
	s_lshr_b32 s9, s20, 1
	s_add_i32 s9, s9, 0xe53
	v_readlane_b32 s8, v255, 46
	s_cmp_lg_u32 s8, 0
	s_cselect_b32 s96, s9, s96
	s_lshl_b64 s[8:9], s[96:97], 2
	v_readlane_b32 s10, v254, 10
	v_readlane_b32 s11, v254, 11
	s_add_u32 s8, s10, s8
	s_addc_u32 s9, s11, s9
	s_bcnt1_i32_b64 s4, s[4:5]
	v_mov_b32_e32 v3, s4
	global_atomic_add v3, v65, v3, s[8:9] sc0
.LBB0_814:
	s_or_b64 exec, exec, s[6:7]
	s_waitcnt lgkmcnt(1)
	v_cvt_f32_u32_e32 v4, v2
	s_waitcnt vmcnt(0)
	v_readfirstlane_b32 s4, v3
	buffer_inv sc1
	v_sub_u32_e32 v3, 0, v2
	v_rcp_iflag_f32_e32 v4, v4
	v_add_u32_e32 v5, s4, v1
	v_mul_f32_e32 v4, 0x4f7ffffe, v4
	v_cvt_u32_f32_e32 v4, v4
	v_mul_lo_u32 v1, v3, v4
	v_mul_hi_u32 v1, v4, v1
	v_add_u32_e32 v1, v4, v1
	v_mul_hi_u32 v1, v5, v1
	v_mul_lo_u32 v3, v1, v2
	v_sub_u32_e32 v3, v5, v3
	v_add_u32_e32 v4, 1, v1
	v_cmp_ge_u32_e32 vcc, v3, v2
	s_nop 1
	v_cndmask_b32_e32 v1, v1, v4, vcc
	v_sub_u32_e32 v4, v3, v2
	v_cndmask_b32_e32 v3, v3, v4, vcc
	v_add_u32_e32 v4, 1, v1
	v_cmp_ge_u32_e32 vcc, v3, v2
	v_add_u32_e32 v3, 1, v5
	s_nop 0
	v_cndmask_b32_e32 v1, v1, v4, vcc
	v_mul_lo_u32 v4, v2, v1
	v_add_u32_e32 v2, v4, v2
	v_cmp_ne_u32_e32 vcc, v3, v2
	s_and_saveexec_b64 s[4:5], vcc
	s_xor_b64 s[4:5], exec, s[4:5]
	s_cbranch_execz .LBB0_828
	v_readlane_b32 s6, v255, 46
	s_cmp_lg_u32 s6, 0
	s_cbranch_scc0 .Lmy_gpoll_d
	s_lshr_b32 s96, s20, 1
	s_add_i32 s96, s96, 0xe53
	s_lshl_b64 s[6:7], s[96:97], 2
	v_readlane_b32 s8, v254, 10
	v_readlane_b32 s9, v254, 11
	s_add_u32 s8, s8, s6
	s_addc_u32 s9, s9, s7
	s_mov_b32 s21, 0
	s_waitcnt lgkmcnt(0)
	s_nop 1

.LBB0_1838:
	v_readlane_b32 s71, v254, 12
	s_mov_b32 s6, s71
	s_waitcnt vmcnt(0)
	s_barrier
	s_and_saveexec_b64 s[0:1], s[26:27]
	s_cbranch_execz .LBB0_1875
	v_readlane_b32 s7, v255, 17
	s_waitcnt vmcnt(0) expcnt(0) lgkmcnt(0)
	s_mov_b64 s[4:5], exec
	v_mov_b32_e32 v0, s7
	v_readlane_b32 s7, v255, 18
	ds_read_b32 v2, v0
	v_mbcnt_lo_u32_b32 v1, s4, 0
	v_mov_b32_e32 v0, s7
	ds_read_b32 v0, v0
	v_mbcnt_hi_u32_b32 v1, s5, v1
	s_lshl_b32 s20, s6, 6
	v_cmp_eq_u32_e32 vcc, 0, v1
	s_and_saveexec_b64 s[6:7], vcc
	s_cbranch_execz .LBB0_1841
	s_add_i32 s96, s20, 0x500
	s_lshr_b32 s9, s20, 1
	s_add_i32 s9, s9, 0xe52
	v_readlane_b32 s8, v255, 46
	s_cmp_lg_u32 s8, 0
	s_cselect_b32 s96, s9, s96
	s_lshl_b64 s[8:9], s[96:97], 2
	v_readlane_b32 s10, v254, 10
	v_readlane_b32 s11, v254, 11
	s_add_u32 s8, s10, s8
	s_addc_u32 s9, s11, s9
	s_bcnt1_i32_b64 s4, s[4:5]
	v_mov_b32_e32 v3, s4
	global_atomic_add v3, v65, v3, s[8:9] sc0
.LBB0_1841:
	s_or_b64 exec, exec, s[6:7]
	s_waitcnt lgkmcnt(1)
	v_cvt_f32_u32_e32 v4, v2
	s_waitcnt vmcnt(0)
	v_readfirstlane_b32 s4, v3
	buffer_inv sc1
	v_sub_u32_e32 v3, 0, v2
	v_rcp_iflag_f32_e32 v4, v4
	v_add_u32_e32 v5, s4, v1
	v_mul_f32_e32 v4, 0x4f7ffffe, v4
	v_cvt_u32_f32_e32 v4, v4
	v_mul_lo_u32 v1, v3, v4
	v_mul_hi_u32 v1, v4, v1
	v_add_u32_e32 v1, v4, v1
	v_mul_hi_u32 v1, v5, v1
	v_mul_lo_u32 v3, v1, v2
	v_sub_u32_e32 v3, v5, v3
	v_add_u32_e32 v4, 1, v1
	v_cmp_ge_u32_e32 vcc, v3, v2
	s_nop 1
	v_cndmask_b32_e32 v1, v1, v4, vcc
	v_sub_u32_e32 v4, v3, v2
	v_cndmask_b32_e32 v3, v3, v4, vcc
	v_add_u32_e32 v4, 1, v1
	v_cmp_ge_u32_e32 vcc, v3, v2
	v_add_u32_e32 v3, 1, v5
	s_nop 0
	v_cndmask_b32_e32 v1, v1, v4, vcc
	v_mul_lo_u32 v4, v2, v1
	v_add_u32_e32 v2, v4, v2
	v_cmp_ne_u32_e32 vcc, v3, v2
	s_and_saveexec_b64 s[4:5], vcc
	s_xor_b64 s[4:5], exec, s[4:5]
	s_cbranch_execz .LBB0_1855
	v_readlane_b32 s6, v255, 46
	s_cmp_lg_u32 s6, 0
	s_cbranch_scc0 .Lmy_gpoll_c
	s_lshr_b32 s96, s20, 1
	s_add_i32 s96, s96, 0xe52
	s_lshl_b64 s[6:7], s[96:97], 2
	v_readlane_b32 s8, v254, 10
	v_readlane_b32 s9, v254, 11
	s_add_u32 s8, s8, s6
	s_addc_u32 s9, s9, s7
	s_mov_b32 s21, 0
	s_waitcnt lgkmcnt(0)
	s_nop 1
	s_cmpk_lt_i32 s2, 0xc0
	s_cbranch_scc1 .Lmy_lpoll_c
	s_waitcnt vmcnt(0)
	s_branch .LBB0_1855

.LBB0_2132:
	s_mov_b32 s4, s71
	s_waitcnt vmcnt(0)
	s_waitcnt lgkmcnt(0)
	s_barrier
	s_and_saveexec_b64 s[6:7], s[26:27]
	v_readlane_b32 s33, v255, 29
	s_cbranch_execz .LBB0_2169
	v_readlane_b32 s0, v255, 17
	s_waitcnt vmcnt(0) expcnt(0) lgkmcnt(0)
	s_mov_b64 s[18:19], exec
	v_mov_b32_e32 v0, s0
	v_readlane_b32 s0, v255, 18
	ds_read_b32 v2, v0
	v_mbcnt_lo_u32_b32 v1, s18, 0
	v_mov_b32_e32 v0, s0
	ds_read_b32 v0, v0
	v_mbcnt_hi_u32_b32 v1, s19, v1
	s_lshl_b32 s4, s4, 6
	v_cmp_eq_u32_e32 vcc, 0, v1
	s_and_saveexec_b64 s[20:21], vcc
	s_cbranch_execz .LBB0_2135
	s_add_i32 s96, s4, 0x500
	s_lshr_b32 s1, s4, 1
	s_add_i32 s1, s1, 0xe51
	v_readlane_b32 s0, v255, 46
	s_cmp_lg_u32 s0, 0
	s_cselect_b32 s96, s1, s96
	s_lshl_b64 s[0:1], s[96:97], 2
	v_readlane_b32 s8, v254, 10
	v_readlane_b32 s9, v254, 11
	s_add_u32 s0, s8, s0
	s_addc_u32 s1, s9, s1
	s_bcnt1_i32_b64 s5, s[18:19]
	v_mov_b32_e32 v3, s5
	global_atomic_add v3, v65, v3, s[0:1] sc0
.LBB0_2135:
	s_or_b64 exec, exec, s[20:21]
	s_waitcnt lgkmcnt(1)
	v_cvt_f32_u32_e32 v4, v2
	s_waitcnt vmcnt(0)
	v_readfirstlane_b32 s0, v3
	buffer_inv sc1
	v_sub_u32_e32 v3, 0, v2
	v_rcp_iflag_f32_e32 v4, v4
	v_add_u32_e32 v5, s0, v1
	v_mul_f32_e32 v4, 0x4f7ffffe, v4
	v_cvt_u32_f32_e32 v4, v4
	v_mul_lo_u32 v1, v3, v4
	v_mul_hi_u32 v1, v4, v1
	v_add_u32_e32 v1, v4, v1
	v_mul_hi_u32 v1, v5, v1
	v_mul_lo_u32 v3, v1, v2
	v_sub_u32_e32 v3, v5, v3
	v_add_u32_e32 v4, 1, v1
	v_cmp_ge_u32_e32 vcc, v3, v2
	s_nop 1
	v_cndmask_b32_e32 v1, v1, v4, vcc
	v_sub_u32_e32 v4, v3, v2
	v_cndmask_b32_e32 v3, v3, v4, vcc
	v_add_u32_e32 v4, 1, v1
	v_cmp_ge_u32_e32 vcc, v3, v2
	v_add_u32_e32 v3, 1, v5
	s_nop 0
	v_cndmask_b32_e32 v1, v1, v4, vcc
	v_mul_lo_u32 v4, v2, v1
	v_add_u32_e32 v2, v4, v2
	v_cmp_ne_u32_e32 vcc, v3, v2
	s_and_saveexec_b64 s[0:1], vcc
	s_xor_b64 s[18:19], exec, s[0:1]
	s_cbranch_execz .LBB0_2149
	v_readlane_b32 s0, v255, 46
	s_cmp_lg_u32 s0, 0
	s_cbranch_scc0 .Lmy_gpoll_b
	s_lshr_b32 s96, s4, 1
	s_add_i32 s96, s96, 0xe51
	s_lshl_b64 s[0:1], s[96:97], 2
	v_readlane_b32 s8, v254, 10
	v_readlane_b32 s9, v254, 11
	s_add_u32 s22, s8, s0
	s_addc_u32 s23, s9, s1
	s_mov_b32 s5, 0
	s_waitcnt lgkmcnt(0)
	s_nop 1

.Lmy_e_skip:
	v_readlane_b32 s7, v255, 17
	s_waitcnt vmcnt(0) expcnt(0) lgkmcnt(0)
	s_mov_b64 s[4:5], exec
	v_mov_b32_e32 v0, s7
	v_readlane_b32 s7, v255, 18
	ds_read_b32 v2, v0
	v_mbcnt_lo_u32_b32 v1, s4, 0
	v_mov_b32_e32 v0, s7
	ds_read_b32 v0, v0
	v_mbcnt_hi_u32_b32 v1, s5, v1
	s_lshl_b32 s20, s6, 6
	v_cmp_eq_u32_e32 vcc, 0, v1
	s_and_saveexec_b64 s[6:7], vcc
	s_cbranch_execz .LBB0_2277
	s_add_i32 s96, s20, 0x500
	s_lshr_b32 s9, s20, 1
	s_add_i32 s9, s9, 0xe54
	v_readlane_b32 s8, v255, 46
	s_cmp_lg_u32 s8, 0
	s_cselect_b32 s96, s9, s96
	s_lshl_b64 s[8:9], s[96:97], 2
	v_readlane_b32 s10, v254, 10
	v_readlane_b32 s11, v254, 11
	s_add_u32 s8, s10, s8
	s_addc_u32 s9, s11, s9
	s_bcnt1_i32_b64 s4, s[4:5]
	v_mov_b32_e32 v3, s4
	global_atomic_add v3, v65, v3, s[8:9] sc0
.LBB0_2277:
	s_or_b64 exec, exec, s[6:7]
	s_waitcnt lgkmcnt(1)
	v_cvt_f32_u32_e32 v4, v2
	s_waitcnt vmcnt(0)
	v_readfirstlane_b32 s4, v3
	buffer_inv sc1
	v_sub_u32_e32 v3, 0, v2
	v_rcp_iflag_f32_e32 v4, v4
	v_add_u32_e32 v5, s4, v1
	v_mul_f32_e32 v4, 0x4f7ffffe, v4
	v_cvt_u32_f32_e32 v4, v4
	v_mul_lo_u32 v1, v3, v4
	v_mul_hi_u32 v1, v4, v1
	v_add_u32_e32 v1, v4, v1
	v_mul_hi_u32 v1, v5, v1
	v_mul_lo_u32 v3, v1, v2
	v_sub_u32_e32 v3, v5, v3
	v_add_u32_e32 v4, 1, v1
	v_cmp_ge_u32_e32 vcc, v3, v2
	s_nop 1
	v_cndmask_b32_e32 v1, v1, v4, vcc
	v_sub_u32_e32 v4, v3, v2
	v_cndmask_b32_e32 v3, v3, v4, vcc
	v_add_u32_e32 v4, 1, v1
	v_cmp_ge_u32_e32 vcc, v3, v2
	v_add_u32_e32 v3, 1, v5
	s_nop 0
	v_cndmask_b32_e32 v1, v1, v4, vcc
	v_mul_lo_u32 v4, v2, v1
	v_add_u32_e32 v2, v4, v2
	v_cmp_ne_u32_e32 vcc, v3, v2
	s_and_saveexec_b64 s[4:5], vcc
	s_xor_b64 s[4:5], exec, s[4:5]
	s_cbranch_execz .LBB0_2291
	v_readlane_b32 s6, v255, 46
	s_cmp_lg_u32 s6, 0
	s_cbranch_scc0 .Lmy_gpoll_e
	s_lshr_b32 s96, s20, 1
	s_add_i32 s96, s96, 0xe54
	s_lshl_b64 s[6:7], s[96:97], 2
	v_readlane_b32 s8, v254, 10
	v_readlane_b32 s9, v254, 11
	s_add_u32 s8, s8, s6
	s_addc_u32 s9, s9, s7
	s_mov_b32 s21, 0
	s_waitcnt lgkmcnt(0)
	s_nop 1
